# modulation GEMV k-loop unrolled by 4 with the 40 loads of a trip in flight (was 10 loads and a full wait per k), on top of v20
# baseline (speedup 1.0000x reference)
.LBB0_70:
	v_lshl_add_u64 v[70:71], v[52:53], 0, s[36:37]
	global_load_dwordx4 v[144:147], v[68:69], off offset:-8
	v_lshl_add_u64 v[84:85], v[50:51], 0, s[36:37]
	v_lshl_add_u64 v[86:87], v[66:67], 0, s[36:37]
	v_lshl_add_u64 v[88:89], v[64:65], 0, s[36:37]
	v_lshl_add_u64 v[90:91], v[62:63], 0, s[36:37]
	v_lshl_add_u64 v[92:93], v[60:61], 0, s[36:37]
	v_lshl_add_u64 v[94:95], v[58:59], 0, s[36:37]
	v_lshl_add_u64 v[96:97], v[56:57], 0, s[36:37]
	v_lshl_add_u64 v[98:99], v[54:55], 0, s[36:37]
	global_load_dword v160, v[70:71], off
	global_load_dword v161, v[84:85], off
	global_load_dword v162, v[86:87], off
	global_load_dword v163, v[88:89], off
	global_load_dword v164, v[90:91], off
	global_load_dword v165, v[92:93], off
	global_load_dword v166, v[94:95], off
	global_load_dword v167, v[96:97], off
	global_load_dword v168, v[98:99], off
	s_add_u32 s36, s36, 4
	s_addc_u32 s37, s37, 0
	v_lshl_add_u64 v[68:69], v[68:69], 0, s[30:31]
	v_lshl_add_u64 v[70:71], v[52:53], 0, s[36:37]
	global_load_dwordx4 v[148:151], v[68:69], off offset:-8
	v_lshl_add_u64 v[84:85], v[50:51], 0, s[36:37]
	v_lshl_add_u64 v[86:87], v[66:67], 0, s[36:37]
	v_lshl_add_u64 v[88:89], v[64:65], 0, s[36:37]
	v_lshl_add_u64 v[90:91], v[62:63], 0, s[36:37]
	v_lshl_add_u64 v[92:93], v[60:61], 0, s[36:37]
	v_lshl_add_u64 v[94:95], v[58:59], 0, s[36:37]
	v_lshl_add_u64 v[96:97], v[56:57], 0, s[36:37]
	v_lshl_add_u64 v[98:99], v[54:55], 0, s[36:37]
	global_load_dword v169, v[70:71], off
	global_load_dword v170, v[84:85], off
	global_load_dword v171, v[86:87], off
	global_load_dword v172, v[88:89], off
	global_load_dword v173, v[90:91], off
	global_load_dword v174, v[92:93], off
	global_load_dword v175, v[94:95], off
	global_load_dword v176, v[96:97], off
	global_load_dword v177, v[98:99], off
	s_add_u32 s36, s36, 4
	s_addc_u32 s37, s37, 0
	v_lshl_add_u64 v[68:69], v[68:69], 0, s[30:31]
	v_lshl_add_u64 v[70:71], v[52:53], 0, s[36:37]
	global_load_dwordx4 v[152:155], v[68:69], off offset:-8
	v_lshl_add_u64 v[84:85], v[50:51], 0, s[36:37]
	v_lshl_add_u64 v[86:87], v[66:67], 0, s[36:37]
	v_lshl_add_u64 v[88:89], v[64:65], 0, s[36:37]
	v_lshl_add_u64 v[90:91], v[62:63], 0, s[36:37]
	v_lshl_add_u64 v[92:93], v[60:61], 0, s[36:37]
	v_lshl_add_u64 v[94:95], v[58:59], 0, s[36:37]
	v_lshl_add_u64 v[96:97], v[56:57], 0, s[36:37]
	v_lshl_add_u64 v[98:99], v[54:55], 0, s[36:37]
	global_load_dword v178, v[70:71], off
	global_load_dword v179, v[84:85], off
	global_load_dword v180, v[86:87], off
	global_load_dword v181, v[88:89], off
	global_load_dword v182, v[90:91], off
	global_load_dword v183, v[92:93], off
	global_load_dword v184, v[94:95], off
	global_load_dword v185, v[96:97], off
	global_load_dword v186, v[98:99], off
	s_add_u32 s36, s36, 4
	s_addc_u32 s37, s37, 0
	v_lshl_add_u64 v[68:69], v[68:69], 0, s[30:31]
	v_lshl_add_u64 v[70:71], v[52:53], 0, s[36:37]
	global_load_dwordx4 v[156:159], v[68:69], off offset:-8
	v_lshl_add_u64 v[84:85], v[50:51], 0, s[36:37]
	v_lshl_add_u64 v[86:87], v[66:67], 0, s[36:37]
	v_lshl_add_u64 v[88:89], v[64:65], 0, s[36:37]
	v_lshl_add_u64 v[90:91], v[62:63], 0, s[36:37]
	v_lshl_add_u64 v[92:93], v[60:61], 0, s[36:37]
	v_lshl_add_u64 v[94:95], v[58:59], 0, s[36:37]
	v_lshl_add_u64 v[96:97], v[56:57], 0, s[36:37]
	v_lshl_add_u64 v[98:99], v[54:55], 0, s[36:37]
	global_load_dword v187, v[70:71], off
	global_load_dword v188, v[84:85], off
	global_load_dword v189, v[86:87], off
	global_load_dword v190, v[88:89], off
	global_load_dword v191, v[90:91], off
	global_load_dword v192, v[92:93], off
	global_load_dword v193, v[94:95], off
	global_load_dword v194, v[96:97], off
	global_load_dword v195, v[98:99], off
	s_add_u32 s36, s36, 4
	s_addc_u32 s37, s37, 0
	v_lshl_add_u64 v[68:69], v[68:69], 0, s[30:31]
	s_waitcnt vmcnt(0)
	v_mul_f32_e32 v70, 0xbfb8aa3b, v160
	v_mul_f32_e32 v71, 0xbfb8aa3b, v161
	v_exp_f32_e32 v70, v70
	v_mul_f32_e32 v84, 0xbfb8aa3b, v162
	v_exp_f32_e32 v71, v71
	v_mul_f32_e32 v85, 0xbfb8aa3b, v163
	v_exp_f32_e32 v84, v84
	v_mul_f32_e32 v86, 0xbfb8aa3b, v164
	v_exp_f32_e32 v85, v85
	v_mul_f32_e32 v87, 0xbfb8aa3b, v165
	v_exp_f32_e32 v86, v86
	v_add_f32_e32 v70, 1.0, v70
	v_mul_f32_e32 v88, 0xbfb8aa3b, v166
	v_exp_f32_e32 v87, v87
	v_add_f32_e32 v71, 1.0, v71
	v_div_scale_f32 v91, s[0:1], v70, v70, 1.0
	v_mul_f32_e32 v89, 0xbfb8aa3b, v167
	v_exp_f32_e32 v88, v88
	v_add_f32_e32 v84, 1.0, v84
	v_div_scale_f32 v93, s[0:1], v71, v71, 1.0
	v_rcp_f32_e32 v117, v91
	v_mul_f32_e32 v90, 0xbfb8aa3b, v168
	v_exp_f32_e32 v89, v89
	v_add_f32_e32 v85, 1.0, v85
	v_div_scale_f32 v95, s[0:1], v84, v84, 1.0
	v_rcp_f32_e32 v118, v93
	v_exp_f32_e32 v90, v90
	v_add_f32_e32 v86, 1.0, v86
	v_div_scale_f32 v97, s[0:1], v85, v85, 1.0
	v_rcp_f32_e32 v119, v95
	v_add_f32_e32 v87, 1.0, v87
	v_div_scale_f32 v99, s[0:1], v86, v86, 1.0
	v_rcp_f32_e32 v120, v97
	v_add_f32_e32 v88, 1.0, v88
	v_div_scale_f32 v109, s[0:1], v87, v87, 1.0
	v_rcp_f32_e32 v121, v99
	v_fma_f32 v126, -v91, v117, 1.0
	v_add_f32_e32 v89, 1.0, v89
	v_div_scale_f32 v92, vcc, 1.0, v70, 1.0
	v_div_scale_f32 v111, s[0:1], v88, v88, 1.0
	v_rcp_f32_e32 v122, v109
	v_fma_f32 v127, -v93, v118, 1.0
	v_fmac_f32_e32 v117, v126, v117
	v_add_f32_e32 v90, 1.0, v90
	v_div_scale_f32 v94, s[18:19], 1.0, v71, 1.0
	v_div_scale_f32 v113, s[0:1], v89, v89, 1.0
	v_rcp_f32_e32 v123, v111
	v_fma_f32 v128, -v95, v119, 1.0
	v_fmac_f32_e32 v118, v127, v118
	v_mul_f32_e32 v126, v92, v117
	v_div_scale_f32 v96, s[20:21], 1.0, v84, 1.0
	v_div_scale_f32 v115, s[0:1], v90, v90, 1.0
	v_rcp_f32_e32 v124, v113
	v_fma_f32 v129, -v97, v120, 1.0
	v_fmac_f32_e32 v119, v128, v119
	v_mul_f32_e32 v127, v94, v118
	v_fma_f32 v135, -v91, v126, v92
	v_div_scale_f32 v98, s[22:23], 1.0, v85, 1.0
	v_rcp_f32_e32 v125, v115
	v_fma_f32 v130, -v99, v121, 1.0
	v_fmac_f32_e32 v120, v129, v120
	v_mul_f32_e32 v128, v96, v119
	v_fma_f32 v136, -v93, v127, v94
	v_fmac_f32_e32 v126, v135, v117
	v_div_scale_f32 v108, s[24:25], 1.0, v86, 1.0
	v_fma_f32 v131, -v109, v122, 1.0
	v_fmac_f32_e32 v121, v130, v121
	v_mul_f32_e32 v129, v98, v120
	v_fma_f32 v137, -v95, v128, v96
	v_fmac_f32_e32 v127, v136, v118
	v_fma_f32 v91, -v91, v126, v92
	v_div_scale_f32 v110, s[26:27], 1.0, v87, 1.0
	v_fma_f32 v132, -v111, v123, 1.0
	v_fmac_f32_e32 v122, v131, v122
	v_mul_f32_e32 v130, v108, v121
	v_fma_f32 v138, -v97, v129, v98
	v_fmac_f32_e32 v128, v137, v119
	v_fma_f32 v92, -v93, v127, v94
	v_div_fmas_f32 v91, v91, v117, v126
	s_mov_b64 vcc, s[18:19]
	v_div_scale_f32 v112, s[16:17], 1.0, v88, 1.0
	v_fma_f32 v133, -v113, v124, 1.0
	v_fmac_f32_e32 v123, v132, v123
	v_mul_f32_e32 v131, v110, v122
	v_fma_f32 v139, -v99, v130, v108
	v_fmac_f32_e32 v129, v138, v120
	v_fma_f32 v93, -v95, v128, v96
	v_div_fixup_f32 v70, v91, v70, 1.0
	v_div_fmas_f32 v91, v92, v118, v127
	s_mov_b64 vcc, s[20:21]
	v_div_scale_f32 v114, s[14:15], 1.0, v89, 1.0
	v_fma_f32 v134, -v115, v125, 1.0
	v_fmac_f32_e32 v124, v133, v124
	v_mul_f32_e32 v132, v112, v123
	v_fma_f32 v140, -v109, v131, v110
	v_fmac_f32_e32 v130, v139, v121
	v_fma_f32 v94, -v97, v129, v98
	v_mul_f32_e32 v70, v160, v70
	v_div_fixup_f32 v71, v91, v71, 1.0
	v_div_fmas_f32 v83, v93, v119, v128
	s_mov_b64 vcc, s[22:23]
	v_div_scale_f32 v116, s[0:1], 1.0, v90, 1.0
	v_fmac_f32_e32 v125, v134, v125
	v_mul_f32_e32 v133, v114, v124
	v_fma_f32 v141, -v111, v132, v112
	v_fmac_f32_e32 v131, v140, v122
	v_fma_f32 v95, -v99, v130, v108
	v_pk_fma_f32 v[34:35], v[144:145], v[70:71], v[34:35] op_sel_hi:[1,0,1]
	v_pk_fma_f32 v[36:37], v[146:147], v[70:71], v[36:37] op_sel_hi:[1,0,1]
	v_mul_f32_e32 v70, v161, v71
	v_div_fixup_f32 v71, v83, v84, 1.0
	v_div_fmas_f32 v83, v94, v120, v129
	s_mov_b64 vcc, s[24:25]
	v_mul_f32_e32 v134, v116, v125
	v_fma_f32 v142, -v113, v133, v114
	v_fmac_f32_e32 v132, v141, v123
	v_fma_f32 v96, -v109, v131, v110
	v_pk_fma_f32 v[30:31], v[144:145], v[70:71], v[30:31] op_sel_hi:[1,0,1]
	v_pk_fma_f32 v[32:33], v[146:147], v[70:71], v[32:33] op_sel_hi:[1,0,1]
	v_mul_f32_e32 v70, v162, v71
	v_div_fixup_f32 v71, v83, v85, 1.0
	v_div_fmas_f32 v83, v95, v121, v130
	s_mov_b64 vcc, s[26:27]
	v_fma_f32 v143, -v115, v134, v116
	v_fmac_f32_e32 v133, v142, v124
	v_fma_f32 v97, -v111, v132, v112
	v_pk_fma_f32 v[26:27], v[144:145], v[70:71], v[26:27] op_sel_hi:[1,0,1]
	v_pk_fma_f32 v[28:29], v[146:147], v[70:71], v[28:29] op_sel_hi:[1,0,1]
	v_mul_f32_e32 v70, v163, v71
	v_div_fixup_f32 v71, v83, v86, 1.0
	v_div_fmas_f32 v83, v96, v122, v131
	s_mov_b64 vcc, s[16:17]
	v_fmac_f32_e32 v134, v143, v125
	v_fma_f32 v98, -v113, v133, v114
	v_pk_fma_f32 v[22:23], v[144:145], v[70:71], v[22:23] op_sel_hi:[1,0,1]
	v_pk_fma_f32 v[24:25], v[146:147], v[70:71], v[24:25] op_sel_hi:[1,0,1]
	v_mul_f32_e32 v70, v164, v71
	v_div_fixup_f32 v71, v83, v87, 1.0
	v_div_fmas_f32 v83, v97, v123, v132
	s_mov_b64 vcc, s[14:15]
	v_fma_f32 v99, -v115, v134, v116
	v_pk_fma_f32 v[18:19], v[144:145], v[70:71], v[18:19] op_sel_hi:[1,0,1]
	v_pk_fma_f32 v[20:21], v[146:147], v[70:71], v[20:21] op_sel_hi:[1,0,1]
	v_mul_f32_e32 v70, v165, v71
	v_div_fixup_f32 v71, v83, v88, 1.0
	v_div_fmas_f32 v83, v98, v124, v133
	s_mov_b64 vcc, s[0:1]
	v_pk_fma_f32 v[14:15], v[144:145], v[70:71], v[14:15] op_sel_hi:[1,0,1]
	v_pk_fma_f32 v[16:17], v[146:147], v[70:71], v[16:17] op_sel_hi:[1,0,1]
	v_mul_f32_e32 v70, v166, v71
	v_div_fixup_f32 v71, v83, v89, 1.0
	v_div_fmas_f32 v83, v99, v125, v134
	v_pk_fma_f32 v[10:11], v[144:145], v[70:71], v[10:11] op_sel_hi:[1,0,1]
	v_pk_fma_f32 v[12:13], v[146:147], v[70:71], v[12:13] op_sel_hi:[1,0,1]
	v_mul_f32_e32 v70, v167, v71
	v_div_fixup_f32 v71, v83, v90, 1.0
	v_pk_fma_f32 v[6:7], v[144:145], v[70:71], v[6:7] op_sel_hi:[1,0,1]
	v_pk_fma_f32 v[8:9], v[146:147], v[70:71], v[8:9] op_sel_hi:[1,0,1]
	v_mul_f32_e32 v70, v168, v71
	v_pk_fma_f32 v[2:3], v[144:145], v[70:71], v[2:3] op_sel_hi:[1,0,1]
	v_pk_fma_f32 v[4:5], v[146:147], v[70:71], v[4:5] op_sel_hi:[1,0,1]
	v_mul_f32_e32 v70, 0xbfb8aa3b, v169
	v_mul_f32_e32 v71, 0xbfb8aa3b, v170
	v_exp_f32_e32 v70, v70
	v_mul_f32_e32 v84, 0xbfb8aa3b, v171
	v_exp_f32_e32 v71, v71
	v_mul_f32_e32 v85, 0xbfb8aa3b, v172
	v_exp_f32_e32 v84, v84
	v_mul_f32_e32 v86, 0xbfb8aa3b, v173
	v_exp_f32_e32 v85, v85
	v_mul_f32_e32 v87, 0xbfb8aa3b, v174
	v_exp_f32_e32 v86, v86
	v_add_f32_e32 v70, 1.0, v70
	v_mul_f32_e32 v88, 0xbfb8aa3b, v175
	v_exp_f32_e32 v87, v87
	v_add_f32_e32 v71, 1.0, v71
	v_div_scale_f32 v91, s[0:1], v70, v70, 1.0
	v_mul_f32_e32 v89, 0xbfb8aa3b, v176
	v_exp_f32_e32 v88, v88
	v_add_f32_e32 v84, 1.0, v84
	v_div_scale_f32 v93, s[0:1], v71, v71, 1.0
	v_rcp_f32_e32 v117, v91
	v_mul_f32_e32 v90, 0xbfb8aa3b, v177
	v_exp_f32_e32 v89, v89
	v_add_f32_e32 v85, 1.0, v85
	v_div_scale_f32 v95, s[0:1], v84, v84, 1.0
	v_rcp_f32_e32 v118, v93
	v_exp_f32_e32 v90, v90
	v_add_f32_e32 v86, 1.0, v86
	v_div_scale_f32 v97, s[0:1], v85, v85, 1.0
	v_rcp_f32_e32 v119, v95
	v_add_f32_e32 v87, 1.0, v87
	v_div_scale_f32 v99, s[0:1], v86, v86, 1.0
	v_rcp_f32_e32 v120, v97
	v_add_f32_e32 v88, 1.0, v88
	v_div_scale_f32 v109, s[0:1], v87, v87, 1.0
	v_rcp_f32_e32 v121, v99
	v_fma_f32 v126, -v91, v117, 1.0
	v_add_f32_e32 v89, 1.0, v89
	v_div_scale_f32 v92, vcc, 1.0, v70, 1.0
	v_div_scale_f32 v111, s[0:1], v88, v88, 1.0
	v_rcp_f32_e32 v122, v109
	v_fma_f32 v127, -v93, v118, 1.0
	v_fmac_f32_e32 v117, v126, v117
	v_add_f32_e32 v90, 1.0, v90
	v_div_scale_f32 v94, s[18:19], 1.0, v71, 1.0
	v_div_scale_f32 v113, s[0:1], v89, v89, 1.0
	v_rcp_f32_e32 v123, v111
	v_fma_f32 v128, -v95, v119, 1.0
	v_fmac_f32_e32 v118, v127, v118
	v_mul_f32_e32 v126, v92, v117
	v_div_scale_f32 v96, s[20:21], 1.0, v84, 1.0
	v_div_scale_f32 v115, s[0:1], v90, v90, 1.0
	v_rcp_f32_e32 v124, v113
	v_fma_f32 v129, -v97, v120, 1.0
	v_fmac_f32_e32 v119, v128, v119
	v_mul_f32_e32 v127, v94, v118
	v_fma_f32 v135, -v91, v126, v92
	v_div_scale_f32 v98, s[22:23], 1.0, v85, 1.0
	v_rcp_f32_e32 v125, v115
	v_fma_f32 v130, -v99, v121, 1.0
	v_fmac_f32_e32 v120, v129, v120
	v_mul_f32_e32 v128, v96, v119
	v_fma_f32 v136, -v93, v127, v94
	v_fmac_f32_e32 v126, v135, v117
	v_div_scale_f32 v108, s[24:25], 1.0, v86, 1.0
	v_fma_f32 v131, -v109, v122, 1.0
	v_fmac_f32_e32 v121, v130, v121
	v_mul_f32_e32 v129, v98, v120
	v_fma_f32 v137, -v95, v128, v96
	v_fmac_f32_e32 v127, v136, v118
	v_fma_f32 v91, -v91, v126, v92
	v_div_scale_f32 v110, s[26:27], 1.0, v87, 1.0
	v_fma_f32 v132, -v111, v123, 1.0
	v_fmac_f32_e32 v122, v131, v122
	v_mul_f32_e32 v130, v108, v121
	v_fma_f32 v138, -v97, v129, v98
	v_fmac_f32_e32 v128, v137, v119
	v_fma_f32 v92, -v93, v127, v94
	v_div_fmas_f32 v91, v91, v117, v126
	s_mov_b64 vcc, s[18:19]
	v_div_scale_f32 v112, s[16:17], 1.0, v88, 1.0
	v_fma_f32 v133, -v113, v124, 1.0
	v_fmac_f32_e32 v123, v132, v123
	v_mul_f32_e32 v131, v110, v122
	v_fma_f32 v139, -v99, v130, v108
	v_fmac_f32_e32 v129, v138, v120
	v_fma_f32 v93, -v95, v128, v96
	v_div_fixup_f32 v70, v91, v70, 1.0
	v_div_fmas_f32 v91, v92, v118, v127
	s_mov_b64 vcc, s[20:21]
	v_div_scale_f32 v114, s[14:15], 1.0, v89, 1.0
	v_fma_f32 v134, -v115, v125, 1.0
	v_fmac_f32_e32 v124, v133, v124
	v_mul_f32_e32 v132, v112, v123
	v_fma_f32 v140, -v109, v131, v110
	v_fmac_f32_e32 v130, v139, v121
	v_fma_f32 v94, -v97, v129, v98
	v_mul_f32_e32 v70, v169, v70
	v_div_fixup_f32 v71, v91, v71, 1.0
	v_div_fmas_f32 v83, v93, v119, v128
	s_mov_b64 vcc, s[22:23]
	v_div_scale_f32 v116, s[0:1], 1.0, v90, 1.0
	v_fmac_f32_e32 v125, v134, v125
	v_mul_f32_e32 v133, v114, v124
	v_fma_f32 v141, -v111, v132, v112
	v_fmac_f32_e32 v131, v140, v122
	v_fma_f32 v95, -v99, v130, v108
	v_pk_fma_f32 v[34:35], v[148:149], v[70:71], v[34:35] op_sel_hi:[1,0,1]
	v_pk_fma_f32 v[36:37], v[150:151], v[70:71], v[36:37] op_sel_hi:[1,0,1]
	v_mul_f32_e32 v70, v170, v71
	v_div_fixup_f32 v71, v83, v84, 1.0
	v_div_fmas_f32 v83, v94, v120, v129
	s_mov_b64 vcc, s[24:25]
	v_mul_f32_e32 v134, v116, v125
	v_fma_f32 v142, -v113, v133, v114
	v_fmac_f32_e32 v132, v141, v123
	v_fma_f32 v96, -v109, v131, v110
	v_pk_fma_f32 v[30:31], v[148:149], v[70:71], v[30:31] op_sel_hi:[1,0,1]
	v_pk_fma_f32 v[32:33], v[150:151], v[70:71], v[32:33] op_sel_hi:[1,0,1]
	v_mul_f32_e32 v70, v171, v71
	v_div_fixup_f32 v71, v83, v85, 1.0
	v_div_fmas_f32 v83, v95, v121, v130
	s_mov_b64 vcc, s[26:27]
	v_fma_f32 v143, -v115, v134, v116
	v_fmac_f32_e32 v133, v142, v124
	v_fma_f32 v97, -v111, v132, v112
	v_pk_fma_f32 v[26:27], v[148:149], v[70:71], v[26:27] op_sel_hi:[1,0,1]
	v_pk_fma_f32 v[28:29], v[150:151], v[70:71], v[28:29] op_sel_hi:[1,0,1]
	v_mul_f32_e32 v70, v172, v71
	v_div_fixup_f32 v71, v83, v86, 1.0
	v_div_fmas_f32 v83, v96, v122, v131
	s_mov_b64 vcc, s[16:17]
	v_fmac_f32_e32 v134, v143, v125
	v_fma_f32 v98, -v113, v133, v114
	v_pk_fma_f32 v[22:23], v[148:149], v[70:71], v[22:23] op_sel_hi:[1,0,1]
	v_pk_fma_f32 v[24:25], v[150:151], v[70:71], v[24:25] op_sel_hi:[1,0,1]
	v_mul_f32_e32 v70, v173, v71
	v_div_fixup_f32 v71, v83, v87, 1.0
	v_div_fmas_f32 v83, v97, v123, v132
	s_mov_b64 vcc, s[14:15]
	v_fma_f32 v99, -v115, v134, v116
	v_pk_fma_f32 v[18:19], v[148:149], v[70:71], v[18:19] op_sel_hi:[1,0,1]
	v_pk_fma_f32 v[20:21], v[150:151], v[70:71], v[20:21] op_sel_hi:[1,0,1]
	v_mul_f32_e32 v70, v174, v71
	v_div_fixup_f32 v71, v83, v88, 1.0
	v_div_fmas_f32 v83, v98, v124, v133
	s_mov_b64 vcc, s[0:1]
	v_pk_fma_f32 v[14:15], v[148:149], v[70:71], v[14:15] op_sel_hi:[1,0,1]
	v_pk_fma_f32 v[16:17], v[150:151], v[70:71], v[16:17] op_sel_hi:[1,0,1]
	v_mul_f32_e32 v70, v175, v71
	v_div_fixup_f32 v71, v83, v89, 1.0
	v_div_fmas_f32 v83, v99, v125, v134
	v_pk_fma_f32 v[10:11], v[148:149], v[70:71], v[10:11] op_sel_hi:[1,0,1]
	v_pk_fma_f32 v[12:13], v[150:151], v[70:71], v[12:13] op_sel_hi:[1,0,1]
	v_mul_f32_e32 v70, v176, v71
	v_div_fixup_f32 v71, v83, v90, 1.0
	v_pk_fma_f32 v[6:7], v[148:149], v[70:71], v[6:7] op_sel_hi:[1,0,1]
	v_pk_fma_f32 v[8:9], v[150:151], v[70:71], v[8:9] op_sel_hi:[1,0,1]
	v_mul_f32_e32 v70, v177, v71
	v_pk_fma_f32 v[2:3], v[148:149], v[70:71], v[2:3] op_sel_hi:[1,0,1]
	v_pk_fma_f32 v[4:5], v[150:151], v[70:71], v[4:5] op_sel_hi:[1,0,1]
	v_mul_f32_e32 v70, 0xbfb8aa3b, v178
	v_mul_f32_e32 v71, 0xbfb8aa3b, v179
	v_exp_f32_e32 v70, v70
	v_mul_f32_e32 v84, 0xbfb8aa3b, v180
	v_exp_f32_e32 v71, v71
	v_mul_f32_e32 v85, 0xbfb8aa3b, v181
	v_exp_f32_e32 v84, v84
	v_mul_f32_e32 v86, 0xbfb8aa3b, v182
	v_exp_f32_e32 v85, v85
	v_mul_f32_e32 v87, 0xbfb8aa3b, v183
	v_exp_f32_e32 v86, v86
	v_add_f32_e32 v70, 1.0, v70
	v_mul_f32_e32 v88, 0xbfb8aa3b, v184
	v_exp_f32_e32 v87, v87
	v_add_f32_e32 v71, 1.0, v71
	v_div_scale_f32 v91, s[0:1], v70, v70, 1.0
	v_mul_f32_e32 v89, 0xbfb8aa3b, v185
	v_exp_f32_e32 v88, v88
	v_add_f32_e32 v84, 1.0, v84
	v_div_scale_f32 v93, s[0:1], v71, v71, 1.0
	v_rcp_f32_e32 v117, v91
	v_mul_f32_e32 v90, 0xbfb8aa3b, v186
	v_exp_f32_e32 v89, v89
	v_add_f32_e32 v85, 1.0, v85
	v_div_scale_f32 v95, s[0:1], v84, v84, 1.0
	v_rcp_f32_e32 v118, v93
	v_exp_f32_e32 v90, v90
	v_add_f32_e32 v86, 1.0, v86
	v_div_scale_f32 v97, s[0:1], v85, v85, 1.0
	v_rcp_f32_e32 v119, v95
	v_add_f32_e32 v87, 1.0, v87
	v_div_scale_f32 v99, s[0:1], v86, v86, 1.0
	v_rcp_f32_e32 v120, v97
	v_add_f32_e32 v88, 1.0, v88
	v_div_scale_f32 v109, s[0:1], v87, v87, 1.0
	v_rcp_f32_e32 v121, v99
	v_fma_f32 v126, -v91, v117, 1.0
	v_add_f32_e32 v89, 1.0, v89
	v_div_scale_f32 v92, vcc, 1.0, v70, 1.0
	v_div_scale_f32 v111, s[0:1], v88, v88, 1.0
	v_rcp_f32_e32 v122, v109
	v_fma_f32 v127, -v93, v118, 1.0
	v_fmac_f32_e32 v117, v126, v117
	v_add_f32_e32 v90, 1.0, v90
	v_div_scale_f32 v94, s[18:19], 1.0, v71, 1.0
	v_div_scale_f32 v113, s[0:1], v89, v89, 1.0
	v_rcp_f32_e32 v123, v111
	v_fma_f32 v128, -v95, v119, 1.0
	v_fmac_f32_e32 v118, v127, v118
	v_mul_f32_e32 v126, v92, v117
	v_div_scale_f32 v96, s[20:21], 1.0, v84, 1.0
	v_div_scale_f32 v115, s[0:1], v90, v90, 1.0
	v_rcp_f32_e32 v124, v113
	v_fma_f32 v129, -v97, v120, 1.0
	v_fmac_f32_e32 v119, v128, v119
	v_mul_f32_e32 v127, v94, v118
	v_fma_f32 v135, -v91, v126, v92
	v_div_scale_f32 v98, s[22:23], 1.0, v85, 1.0
	v_rcp_f32_e32 v125, v115
	v_fma_f32 v130, -v99, v121, 1.0
	v_fmac_f32_e32 v120, v129, v120
	v_mul_f32_e32 v128, v96, v119
	v_fma_f32 v136, -v93, v127, v94
	v_fmac_f32_e32 v126, v135, v117
	v_div_scale_f32 v108, s[24:25], 1.0, v86, 1.0
	v_fma_f32 v131, -v109, v122, 1.0
	v_fmac_f32_e32 v121, v130, v121
	v_mul_f32_e32 v129, v98, v120
	v_fma_f32 v137, -v95, v128, v96
	v_fmac_f32_e32 v127, v136, v118
	v_fma_f32 v91, -v91, v126, v92
	v_div_scale_f32 v110, s[26:27], 1.0, v87, 1.0
	v_fma_f32 v132, -v111, v123, 1.0
	v_fmac_f32_e32 v122, v131, v122
	v_mul_f32_e32 v130, v108, v121
	v_fma_f32 v138, -v97, v129, v98
	v_fmac_f32_e32 v128, v137, v119
	v_fma_f32 v92, -v93, v127, v94
	v_div_fmas_f32 v91, v91, v117, v126
	s_mov_b64 vcc, s[18:19]
	v_div_scale_f32 v112, s[16:17], 1.0, v88, 1.0
	v_fma_f32 v133, -v113, v124, 1.0
	v_fmac_f32_e32 v123, v132, v123
	v_mul_f32_e32 v131, v110, v122
	v_fma_f32 v139, -v99, v130, v108
	v_fmac_f32_e32 v129, v138, v120
	v_fma_f32 v93, -v95, v128, v96
	v_div_fixup_f32 v70, v91, v70, 1.0
	v_div_fmas_f32 v91, v92, v118, v127
	s_mov_b64 vcc, s[20:21]
	v_div_scale_f32 v114, s[14:15], 1.0, v89, 1.0
	v_fma_f32 v134, -v115, v125, 1.0
	v_fmac_f32_e32 v124, v133, v124
	v_mul_f32_e32 v132, v112, v123
	v_fma_f32 v140, -v109, v131, v110
	v_fmac_f32_e32 v130, v139, v121
	v_fma_f32 v94, -v97, v129, v98
	v_mul_f32_e32 v70, v178, v70
	v_div_fixup_f32 v71, v91, v71, 1.0
	v_div_fmas_f32 v83, v93, v119, v128
	s_mov_b64 vcc, s[22:23]
	v_div_scale_f32 v116, s[0:1], 1.0, v90, 1.0
	v_fmac_f32_e32 v125, v134, v125
	v_mul_f32_e32 v133, v114, v124
	v_fma_f32 v141, -v111, v132, v112
	v_fmac_f32_e32 v131, v140, v122
	v_fma_f32 v95, -v99, v130, v108
	v_pk_fma_f32 v[34:35], v[152:153], v[70:71], v[34:35] op_sel_hi:[1,0,1]
	v_pk_fma_f32 v[36:37], v[154:155], v[70:71], v[36:37] op_sel_hi:[1,0,1]
	v_mul_f32_e32 v70, v179, v71
	v_div_fixup_f32 v71, v83, v84, 1.0
	v_div_fmas_f32 v83, v94, v120, v129
	s_mov_b64 vcc, s[24:25]
	v_mul_f32_e32 v134, v116, v125
	v_fma_f32 v142, -v113, v133, v114
	v_fmac_f32_e32 v132, v141, v123
	v_fma_f32 v96, -v109, v131, v110
	v_pk_fma_f32 v[30:31], v[152:153], v[70:71], v[30:31] op_sel_hi:[1,0,1]
	v_pk_fma_f32 v[32:33], v[154:155], v[70:71], v[32:33] op_sel_hi:[1,0,1]
	v_mul_f32_e32 v70, v180, v71
	v_div_fixup_f32 v71, v83, v85, 1.0
	v_div_fmas_f32 v83, v95, v121, v130
	s_mov_b64 vcc, s[26:27]
	v_fma_f32 v143, -v115, v134, v116
	v_fmac_f32_e32 v133, v142, v124
	v_fma_f32 v97, -v111, v132, v112
	v_pk_fma_f32 v[26:27], v[152:153], v[70:71], v[26:27] op_sel_hi:[1,0,1]
	v_pk_fma_f32 v[28:29], v[154:155], v[70:71], v[28:29] op_sel_hi:[1,0,1]
	v_mul_f32_e32 v70, v181, v71
	v_div_fixup_f32 v71, v83, v86, 1.0
	v_div_fmas_f32 v83, v96, v122, v131
	s_mov_b64 vcc, s[16:17]
	v_fmac_f32_e32 v134, v143, v125
	v_fma_f32 v98, -v113, v133, v114
	v_pk_fma_f32 v[22:23], v[152:153], v[70:71], v[22:23] op_sel_hi:[1,0,1]
	v_pk_fma_f32 v[24:25], v[154:155], v[70:71], v[24:25] op_sel_hi:[1,0,1]
	v_mul_f32_e32 v70, v182, v71
	v_div_fixup_f32 v71, v83, v87, 1.0
	v_div_fmas_f32 v83, v97, v123, v132
	s_mov_b64 vcc, s[14:15]
	v_fma_f32 v99, -v115, v134, v116
	v_pk_fma_f32 v[18:19], v[152:153], v[70:71], v[18:19] op_sel_hi:[1,0,1]
	v_pk_fma_f32 v[20:21], v[154:155], v[70:71], v[20:21] op_sel_hi:[1,0,1]
	v_mul_f32_e32 v70, v183, v71
	v_div_fixup_f32 v71, v83, v88, 1.0
	v_div_fmas_f32 v83, v98, v124, v133
	s_mov_b64 vcc, s[0:1]
	v_pk_fma_f32 v[14:15], v[152:153], v[70:71], v[14:15] op_sel_hi:[1,0,1]
	v_pk_fma_f32 v[16:17], v[154:155], v[70:71], v[16:17] op_sel_hi:[1,0,1]
	v_mul_f32_e32 v70, v184, v71
	v_div_fixup_f32 v71, v83, v89, 1.0
	v_div_fmas_f32 v83, v99, v125, v134
	v_pk_fma_f32 v[10:11], v[152:153], v[70:71], v[10:11] op_sel_hi:[1,0,1]
	v_pk_fma_f32 v[12:13], v[154:155], v[70:71], v[12:13] op_sel_hi:[1,0,1]
	v_mul_f32_e32 v70, v185, v71
	v_div_fixup_f32 v71, v83, v90, 1.0
	v_pk_fma_f32 v[6:7], v[152:153], v[70:71], v[6:7] op_sel_hi:[1,0,1]
	v_pk_fma_f32 v[8:9], v[154:155], v[70:71], v[8:9] op_sel_hi:[1,0,1]
	v_mul_f32_e32 v70, v186, v71
	v_pk_fma_f32 v[2:3], v[152:153], v[70:71], v[2:3] op_sel_hi:[1,0,1]
	v_pk_fma_f32 v[4:5], v[154:155], v[70:71], v[4:5] op_sel_hi:[1,0,1]
	v_mul_f32_e32 v70, 0xbfb8aa3b, v187
	v_mul_f32_e32 v71, 0xbfb8aa3b, v188
	v_exp_f32_e32 v70, v70
	v_mul_f32_e32 v84, 0xbfb8aa3b, v189
	v_exp_f32_e32 v71, v71
	v_mul_f32_e32 v85, 0xbfb8aa3b, v190
	v_exp_f32_e32 v84, v84
	v_mul_f32_e32 v86, 0xbfb8aa3b, v191
	v_exp_f32_e32 v85, v85
	v_mul_f32_e32 v87, 0xbfb8aa3b, v192
	v_exp_f32_e32 v86, v86
	v_add_f32_e32 v70, 1.0, v70
	v_mul_f32_e32 v88, 0xbfb8aa3b, v193
	v_exp_f32_e32 v87, v87
	v_add_f32_e32 v71, 1.0, v71
	v_div_scale_f32 v91, s[0:1], v70, v70, 1.0
	v_mul_f32_e32 v89, 0xbfb8aa3b, v194
	v_exp_f32_e32 v88, v88
	v_add_f32_e32 v84, 1.0, v84
	v_div_scale_f32 v93, s[0:1], v71, v71, 1.0
	v_rcp_f32_e32 v117, v91
	v_mul_f32_e32 v90, 0xbfb8aa3b, v195
	v_exp_f32_e32 v89, v89
	v_add_f32_e32 v85, 1.0, v85
	v_div_scale_f32 v95, s[0:1], v84, v84, 1.0
	v_rcp_f32_e32 v118, v93
	v_exp_f32_e32 v90, v90
	v_add_f32_e32 v86, 1.0, v86
	v_div_scale_f32 v97, s[0:1], v85, v85, 1.0
	v_rcp_f32_e32 v119, v95
	v_add_f32_e32 v87, 1.0, v87
	v_div_scale_f32 v99, s[0:1], v86, v86, 1.0
	v_rcp_f32_e32 v120, v97
	v_add_f32_e32 v88, 1.0, v88
	v_div_scale_f32 v109, s[0:1], v87, v87, 1.0
	v_rcp_f32_e32 v121, v99
	v_fma_f32 v126, -v91, v117, 1.0
	v_add_f32_e32 v89, 1.0, v89
	v_div_scale_f32 v92, vcc, 1.0, v70, 1.0
	v_div_scale_f32 v111, s[0:1], v88, v88, 1.0
	v_rcp_f32_e32 v122, v109
	v_fma_f32 v127, -v93, v118, 1.0
	v_fmac_f32_e32 v117, v126, v117
	v_add_f32_e32 v90, 1.0, v90
	v_div_scale_f32 v94, s[18:19], 1.0, v71, 1.0
	v_div_scale_f32 v113, s[0:1], v89, v89, 1.0
	v_rcp_f32_e32 v123, v111
	v_fma_f32 v128, -v95, v119, 1.0
	v_fmac_f32_e32 v118, v127, v118
	v_mul_f32_e32 v126, v92, v117
	v_div_scale_f32 v96, s[20:21], 1.0, v84, 1.0
	v_div_scale_f32 v115, s[0:1], v90, v90, 1.0
	v_rcp_f32_e32 v124, v113
	v_fma_f32 v129, -v97, v120, 1.0
	v_fmac_f32_e32 v119, v128, v119
	v_mul_f32_e32 v127, v94, v118
	v_fma_f32 v135, -v91, v126, v92
	v_div_scale_f32 v98, s[22:23], 1.0, v85, 1.0
	v_rcp_f32_e32 v125, v115
	v_fma_f32 v130, -v99, v121, 1.0
	v_fmac_f32_e32 v120, v129, v120
	v_mul_f32_e32 v128, v96, v119
	v_fma_f32 v136, -v93, v127, v94
	v_fmac_f32_e32 v126, v135, v117
	v_div_scale_f32 v108, s[24:25], 1.0, v86, 1.0
	v_fma_f32 v131, -v109, v122, 1.0
	v_fmac_f32_e32 v121, v130, v121
	v_mul_f32_e32 v129, v98, v120
	v_fma_f32 v137, -v95, v128, v96
	v_fmac_f32_e32 v127, v136, v118
	v_fma_f32 v91, -v91, v126, v92
	v_div_scale_f32 v110, s[26:27], 1.0, v87, 1.0
	v_fma_f32 v132, -v111, v123, 1.0
	v_fmac_f32_e32 v122, v131, v122
	v_mul_f32_e32 v130, v108, v121
	v_fma_f32 v138, -v97, v129, v98
	v_fmac_f32_e32 v128, v137, v119
	v_fma_f32 v92, -v93, v127, v94
	v_div_fmas_f32 v91, v91, v117, v126
	s_mov_b64 vcc, s[18:19]
	v_div_scale_f32 v112, s[16:17], 1.0, v88, 1.0
	v_fma_f32 v133, -v113, v124, 1.0
	v_fmac_f32_e32 v123, v132, v123
	v_mul_f32_e32 v131, v110, v122
	v_fma_f32 v139, -v99, v130, v108
	v_fmac_f32_e32 v129, v138, v120
	v_fma_f32 v93, -v95, v128, v96
	v_div_fixup_f32 v70, v91, v70, 1.0
	v_div_fmas_f32 v91, v92, v118, v127
	s_mov_b64 vcc, s[20:21]
	v_div_scale_f32 v114, s[14:15], 1.0, v89, 1.0
	v_fma_f32 v134, -v115, v125, 1.0
	v_fmac_f32_e32 v124, v133, v124
	v_mul_f32_e32 v132, v112, v123
	v_fma_f32 v140, -v109, v131, v110
	v_fmac_f32_e32 v130, v139, v121
	v_fma_f32 v94, -v97, v129, v98
	v_mul_f32_e32 v70, v187, v70
	v_div_fixup_f32 v71, v91, v71, 1.0
	v_div_fmas_f32 v83, v93, v119, v128
	s_mov_b64 vcc, s[22:23]
	v_div_scale_f32 v116, s[0:1], 1.0, v90, 1.0
	v_fmac_f32_e32 v125, v134, v125
	v_mul_f32_e32 v133, v114, v124
	v_fma_f32 v141, -v111, v132, v112
	v_fmac_f32_e32 v131, v140, v122
	v_fma_f32 v95, -v99, v130, v108
	v_pk_fma_f32 v[34:35], v[156:157], v[70:71], v[34:35] op_sel_hi:[1,0,1]
	v_pk_fma_f32 v[36:37], v[158:159], v[70:71], v[36:37] op_sel_hi:[1,0,1]
	v_mul_f32_e32 v70, v188, v71
	v_div_fixup_f32 v71, v83, v84, 1.0
	v_div_fmas_f32 v83, v94, v120, v129
	s_mov_b64 vcc, s[24:25]
	v_mul_f32_e32 v134, v116, v125
	v_fma_f32 v142, -v113, v133, v114
	v_fmac_f32_e32 v132, v141, v123
	v_fma_f32 v96, -v109, v131, v110
	v_pk_fma_f32 v[30:31], v[156:157], v[70:71], v[30:31] op_sel_hi:[1,0,1]
	v_pk_fma_f32 v[32:33], v[158:159], v[70:71], v[32:33] op_sel_hi:[1,0,1]
	v_mul_f32_e32 v70, v189, v71
	v_div_fixup_f32 v71, v83, v85, 1.0
	v_div_fmas_f32 v83, v95, v121, v130
	s_mov_b64 vcc, s[26:27]
	v_fma_f32 v143, -v115, v134, v116
	v_fmac_f32_e32 v133, v142, v124
	v_fma_f32 v97, -v111, v132, v112
	v_pk_fma_f32 v[26:27], v[156:157], v[70:71], v[26:27] op_sel_hi:[1,0,1]
	v_pk_fma_f32 v[28:29], v[158:159], v[70:71], v[28:29] op_sel_hi:[1,0,1]
	v_mul_f32_e32 v70, v190, v71
	v_div_fixup_f32 v71, v83, v86, 1.0
	v_div_fmas_f32 v83, v96, v122, v131
	s_mov_b64 vcc, s[16:17]
	v_fmac_f32_e32 v134, v143, v125
	v_fma_f32 v98, -v113, v133, v114
	v_pk_fma_f32 v[22:23], v[156:157], v[70:71], v[22:23] op_sel_hi:[1,0,1]
	v_pk_fma_f32 v[24:25], v[158:159], v[70:71], v[24:25] op_sel_hi:[1,0,1]
	v_mul_f32_e32 v70, v191, v71
	v_div_fixup_f32 v71, v83, v87, 1.0
	v_div_fmas_f32 v83, v97, v123, v132
	s_mov_b64 vcc, s[14:15]
	v_fma_f32 v99, -v115, v134, v116
	v_pk_fma_f32 v[18:19], v[156:157], v[70:71], v[18:19] op_sel_hi:[1,0,1]
	v_pk_fma_f32 v[20:21], v[158:159], v[70:71], v[20:21] op_sel_hi:[1,0,1]
	v_mul_f32_e32 v70, v192, v71
	v_div_fixup_f32 v71, v83, v88, 1.0
	v_div_fmas_f32 v83, v98, v124, v133
	s_mov_b64 vcc, s[0:1]
	v_pk_fma_f32 v[14:15], v[156:157], v[70:71], v[14:15] op_sel_hi:[1,0,1]
	v_pk_fma_f32 v[16:17], v[158:159], v[70:71], v[16:17] op_sel_hi:[1,0,1]
	v_mul_f32_e32 v70, v193, v71
	v_div_fixup_f32 v71, v83, v89, 1.0
	v_div_fmas_f32 v83, v99, v125, v134
	v_pk_fma_f32 v[10:11], v[156:157], v[70:71], v[10:11] op_sel_hi:[1,0,1]
	v_pk_fma_f32 v[12:13], v[158:159], v[70:71], v[12:13] op_sel_hi:[1,0,1]
	v_mul_f32_e32 v70, v194, v71
	v_div_fixup_f32 v71, v83, v90, 1.0
	v_pk_fma_f32 v[6:7], v[156:157], v[70:71], v[6:7] op_sel_hi:[1,0,1]
	v_pk_fma_f32 v[8:9], v[158:159], v[70:71], v[8:9] op_sel_hi:[1,0,1]
	v_mul_f32_e32 v70, v195, v71
	v_pk_fma_f32 v[2:3], v[156:157], v[70:71], v[2:3] op_sel_hi:[1,0,1]
	v_pk_fma_f32 v[4:5], v[158:159], v[70:71], v[4:5] op_sel_hi:[1,0,1]
	s_cmpk_eq_i32 s36, 0x80
	s_cbranch_scc0 .LBB0_70
	s_waitcnt lgkmcnt(0)
	s_barrier
	ds_write_b128 v82, v[34:37]
	ds_write_b128 v82, v[30:33] offset:1024
	ds_write_b128 v82, v[26:29] offset:2048
	ds_write_b128 v82, v[22:25] offset:3072
	ds_write_b128 v82, v[18:21] offset:4096
	ds_write_b128 v82, v[14:17] offset:5120
	ds_write_b128 v82, v[10:13] offset:6144
	ds_write_b128 v82, v[6:9] offset:7168
	ds_write_b128 v82, v[2:5] offset:8192
	s_waitcnt lgkmcnt(0)
	s_barrier
	s_and_saveexec_b64 s[0:1], s[4:5]
	s_cbranch_execz .LBB0_68
	s_lshl_b32 s14, s41, 2
	s_or_b32 s14, s14, s42
	s_mul_i32 s14, s14, 9
	s_ashr_i32 s15, s14, 31
	v_lshl_add_u64 v[2:3], s[34:35], 2, v[46:47]
	s_mov_b64 s[18:19], -1
	v_mov_b32_e32 v5, v42
	v_mov_b32_e32 v4, v72
	s_and_saveexec_b64 s[16:17], s[6:7]
	s_cbranch_execz .LBB0_82
	v_mov_b32_e32 v6, 0
	v_mov_b64_e32 v[4:5], v[42:43]
	s_and_saveexec_b64 s[18:19], s[8:9]
	s_cbranch_execz .LBB0_77
	s_mov_b32 s22, 0
	s_mov_b64 s[20:21], 0
	v_mov_b32_e32 v6, v74
	v_mov_b32_e32 v7, v72
	v_mov_b64_e32 v[4:5], v[42:43]
